# v38: v32 + all nine GEMM K-loop heads aligned to 64 B (s_nop padding in the preheaders; code placement only)
# speedup vs baseline: 1.0069x; 1.0057x over previous
; template <class Epi, class Sched, bool ALIGN_EPI = false, bool SP2 = false>
; __device__ __forceinline__ void gemm_phase(PG8_LAS unsigned char* lds, const Gemm g, const Sched& S, const Epi& E) {
;     ...
;         const char* nA = has_next ? (const char*)g.A + (size_t)nxt.pm * tstep + (size_t)nxt.kt0 * kstep : cA; const char* nB = has_next ? (const char*)g.Bt + (size_t)nxt.pn * tstep + (size_t)nxt.kt0 * kstep : cB;
;         const int nt = cur.nkt;
;         for (int t = 0; t < nt; t += 2) {
;             const bool last = (t == nt - 2);
;             const char* a1 = cA + (size_t)(t + 1) * kstep;
;             const char* a2 = last ? nA : cA + (size_t)(t + 2) * kstep; const char* b2 = last ? nB : cB + (size_t)(t + 2) * kstep;
;     ...
; #pragma unroll
;         for (int a = 0; a < 2; ++a)
; #pragma unroll
;             for (int b = 0; b < 2; ++b)
; #pragma unroll
;                 for (int m = 0; m < 4; ++m)
; #pragma unroll
;                     for (int n = 0; n < 2; ++n) acc[a][b][m][n] = (f32x4){0.f, 0.f, 0.f, 0.f};
;         cur = nxt; cA = nA; cB = nB; ++ui;
.LBB0_293:
	s_ashr_i32 s17, s16, 31
	s_lshl_b64 s[18:19], s[16:17], 19
	s_add_u32 s18, s0, s18
	s_addc_u32 s19, s28, s19
	s_and_b64 s[20:21], s[4:5], exec
	s_cselect_b32 s17, s19, s25
	s_cselect_b32 s42, s18, s24
	s_ashr_i32 s15, s14, 31
	s_lshl_b64 s[20:21], s[14:15], 19
	s_add_u32 s20, s29, s20
	s_addc_u32 s21, s30, s21
	s_and_b64 s[26:27], s[4:5], exec
	s_cselect_b32 s15, s21, s3
	s_cselect_b32 s43, s20, s2
	s_add_u32 s45, s2, 0x100
	s_addc_u32 s46, s3, 0
	s_add_u32 s2, s24, 0x40080
	v_mov_b32_e32 v0, 0
	s_addc_u32 s3, s25, 0
	s_mov_b32 s47, -2
	v_mov_b64_e32 v[0:1], 0
	v_mov_b64_e32 v[2:3], 0
	v_mov_b64_e32 v[8:9], 0
	v_mov_b64_e32 v[10:11], 0
	v_mov_b64_e32 v[16:17], 0
	v_mov_b64_e32 v[18:19], 0
	v_mov_b64_e32 v[24:25], 0
	v_mov_b64_e32 v[26:27], 0
	v_mov_b64_e32 v[32:33], 0
	v_mov_b64_e32 v[34:35], 0
	v_mov_b64_e32 v[40:41], 0
	v_mov_b64_e32 v[42:43], 0
	v_mov_b64_e32 v[48:49], 0
	v_mov_b64_e32 v[50:51], 0
	v_mov_b64_e32 v[56:57], 0
	v_mov_b64_e32 v[58:59], 0
	v_mov_b64_e32 v[4:5], 0
	v_mov_b64_e32 v[6:7], 0
	v_mov_b64_e32 v[12:13], 0
	v_mov_b64_e32 v[14:15], 0
	v_mov_b64_e32 v[20:21], 0
	v_mov_b64_e32 v[22:23], 0
	v_mov_b64_e32 v[28:29], 0
	v_mov_b64_e32 v[30:31], 0
	v_mov_b64_e32 v[36:37], 0
	v_mov_b64_e32 v[38:39], 0
	v_mov_b64_e32 v[44:45], 0
	v_mov_b64_e32 v[46:47], 0
	v_mov_b64_e32 v[52:53], 0
	v_mov_b64_e32 v[54:55], 0
	v_mov_b64_e32 v[60:61], 0
	v_mov_b64_e32 v[62:63], 0
	v_mov_b64_e32 v[64:65], 0
	v_mov_b64_e32 v[66:67], 0
	v_mov_b64_e32 v[72:73], 0
	v_mov_b64_e32 v[74:75], 0
	v_mov_b64_e32 v[80:81], 0
	v_mov_b64_e32 v[82:83], 0
	v_mov_b64_e32 v[88:89], 0
	v_mov_b64_e32 v[90:91], 0
	v_mov_b64_e32 v[96:97], 0
	v_mov_b64_e32 v[98:99], 0
	v_mov_b64_e32 v[104:105], 0
	v_mov_b64_e32 v[106:107], 0
	v_mov_b64_e32 v[112:113], 0
	v_mov_b64_e32 v[114:115], 0
	v_mov_b64_e32 v[120:121], 0
	v_mov_b64_e32 v[122:123], 0
	v_mov_b64_e32 v[68:69], 0
	v_mov_b64_e32 v[70:71], 0
	v_mov_b64_e32 v[76:77], 0
	v_mov_b64_e32 v[78:79], 0
	v_mov_b64_e32 v[84:85], 0
	v_mov_b64_e32 v[86:87], 0
	v_mov_b64_e32 v[92:93], 0
	v_mov_b64_e32 v[94:95], 0
	v_mov_b64_e32 v[100:101], 0
	v_mov_b64_e32 v[102:103], 0
	v_mov_b64_e32 v[108:109], 0
	v_mov_b64_e32 v[110:111], 0
	v_mov_b64_e32 v[116:117], 0
	v_mov_b64_e32 v[118:119], 0
	v_mov_b64_e32 v[124:125], 0
	v_mov_b64_e32 v[126:127], 0
	s_mov_b64 s[52:53], 0x80
	s_nop 0
	s_nop 0
	s_nop 0
	s_nop 0
	s_nop 0
	s_nop 0
	s_nop 0
	s_nop 0
	s_nop 0
	s_nop 0
	s_nop 0
	s_nop 0
	s_nop 0
	s_nop 0

; template <class Epi, class Sched, bool ALIGN_EPI = false, bool SP2 = false>
; __device__ __forceinline__ void gemm_phase(PG8_LAS unsigned char* lds, const Gemm g, const Sched& S, const Epi& E) {
;     ...
;         const int nt = cur.nkt;
;         for (int t = 0; t < nt; t += 2) {
;             const bool last = (t == nt - 2);
;     ...
; #pragma unroll
;         for (int a = 0; a < 2; ++a)
; #pragma unroll
;             for (int b = 0; b < 2; ++b)
; #pragma unroll
;                 for (int m = 0; m < 4; ++m)
; #pragma unroll
;                     for (int n = 0; n < 2; ++n) acc[a][b][m][n] = (f32x4){0.f, 0.f, 0.f, 0.f};
;         cur = nxt; cA = nA; cB = nB; ++ui;
.LBB0_376:
	s_add_i32 s25, s27, -2
	s_add_u32 s58, s34, 0x100
	v_mov_b32_e32 v0, 0
	s_addc_u32 s59, s35, 0
	s_mov_b32 s34, 0
	v_mov_b64_e32 v[0:1], 0
	v_mov_b64_e32 v[2:3], 0
	v_mov_b64_e32 v[4:5], 0
	v_mov_b64_e32 v[6:7], 0
	v_mov_b64_e32 v[8:9], 0
	v_mov_b64_e32 v[10:11], 0
	v_mov_b64_e32 v[12:13], 0
	v_mov_b64_e32 v[14:15], 0
	v_mov_b64_e32 v[16:17], 0
	v_mov_b64_e32 v[18:19], 0
	v_mov_b64_e32 v[20:21], 0
	v_mov_b64_e32 v[22:23], 0
	v_mov_b64_e32 v[24:25], 0
	v_mov_b64_e32 v[26:27], 0
	v_mov_b64_e32 v[28:29], 0
	v_mov_b64_e32 v[30:31], 0
	v_mov_b64_e32 v[32:33], 0
	v_mov_b64_e32 v[34:35], 0
	v_mov_b64_e32 v[36:37], 0
	v_mov_b64_e32 v[38:39], 0
	v_mov_b64_e32 v[40:41], 0
	v_mov_b64_e32 v[42:43], 0
	v_mov_b64_e32 v[44:45], 0
	v_mov_b64_e32 v[46:47], 0
	v_mov_b64_e32 v[48:49], 0
	v_mov_b64_e32 v[50:51], 0
	v_mov_b64_e32 v[52:53], 0
	v_mov_b64_e32 v[54:55], 0
	v_mov_b64_e32 v[56:57], 0
	v_mov_b64_e32 v[58:59], 0
	v_mov_b64_e32 v[60:61], 0
	v_mov_b64_e32 v[62:63], 0
	v_mov_b64_e32 v[64:65], 0
	v_mov_b64_e32 v[66:67], 0
	v_mov_b64_e32 v[68:69], 0
	v_mov_b64_e32 v[70:71], 0
	v_mov_b64_e32 v[72:73], 0
	v_mov_b64_e32 v[74:75], 0
	v_mov_b64_e32 v[76:77], 0
	v_mov_b64_e32 v[78:79], 0
	v_mov_b64_e32 v[80:81], 0
	v_mov_b64_e32 v[82:83], 0
	v_mov_b64_e32 v[84:85], 0
	v_mov_b64_e32 v[86:87], 0
	v_mov_b64_e32 v[88:89], 0
	v_mov_b64_e32 v[90:91], 0
	v_mov_b64_e32 v[92:93], 0
	v_mov_b64_e32 v[94:95], 0
	v_mov_b64_e32 v[96:97], 0
	v_mov_b64_e32 v[98:99], 0
	v_mov_b64_e32 v[100:101], 0
	v_mov_b64_e32 v[102:103], 0
	v_mov_b64_e32 v[104:105], 0
	v_mov_b64_e32 v[106:107], 0
	v_mov_b64_e32 v[108:109], 0
	v_mov_b64_e32 v[110:111], 0
	v_mov_b64_e32 v[112:113], 0
	v_mov_b64_e32 v[114:115], 0
	v_mov_b64_e32 v[116:117], 0
	v_mov_b64_e32 v[118:119], 0
	v_mov_b64_e32 v[120:121], 0
	v_mov_b64_e32 v[122:123], 0
	v_mov_b64_e32 v[124:125], 0
	v_mov_b64_e32 v[126:127], 0
	s_mov_b64 s[66:67], 0x80
	s_nop 0
	s_nop 0
	s_nop 0
	s_nop 0
	s_nop 0
	s_nop 0
	s_nop 0
	s_nop 0
	s_nop 0
	s_nop 0

; template <class Epi, class Sched, bool ALIGN_EPI = false, bool SP2 = false>
; __device__ __forceinline__ void gemm_phase(PG8_LAS unsigned char* lds, const Gemm g, const Sched& S, const Epi& E) {
;     ...
; #pragma unroll
;         for (int a = 0; a < 2; ++a)
; #pragma unroll
;             for (int b = 0; b < 2; ++b)
; #pragma unroll
;                 for (int m = 0; m < 4; ++m)
; #pragma unroll
;                     for (int n = 0; n < 2; ++n) acc[a][b][m][n] = (f32x4){0.f, 0.f, 0.f, 0.f};
;         cur = nxt; cA = nA; cB = nB; ++ui;
.LBB0_452:
	s_add_u32 s43, s18, 0x100
	v_mov_b32_e32 v0, 0
	s_addc_u32 s45, s19, 0
	s_mov_b32 s46, -2
	s_waitcnt lgkmcnt(0)
	v_mov_b64_e32 v[0:1], 0
	v_mov_b64_e32 v[2:3], 0
	v_mov_b64_e32 v[4:5], 0
	v_mov_b64_e32 v[6:7], 0
	v_mov_b64_e32 v[16:17], 0
	v_mov_b64_e32 v[18:19], 0
	v_mov_b64_e32 v[20:21], 0
	v_mov_b64_e32 v[22:23], 0
	v_mov_b64_e32 v[32:33], 0
	v_mov_b64_e32 v[34:35], 0
	v_mov_b64_e32 v[36:37], 0
	v_mov_b64_e32 v[38:39], 0
	v_mov_b64_e32 v[48:49], 0
	v_mov_b64_e32 v[50:51], 0
	v_mov_b64_e32 v[52:53], 0
	v_mov_b64_e32 v[54:55], 0
	v_mov_b64_e32 v[8:9], 0
	v_mov_b64_e32 v[10:11], 0
	v_mov_b64_e32 v[12:13], 0
	v_mov_b64_e32 v[14:15], 0
	v_mov_b64_e32 v[24:25], 0
	v_mov_b64_e32 v[26:27], 0
	v_mov_b64_e32 v[28:29], 0
	v_mov_b64_e32 v[30:31], 0
	v_mov_b64_e32 v[40:41], 0
	v_mov_b64_e32 v[42:43], 0
	v_mov_b64_e32 v[44:45], 0
	v_mov_b64_e32 v[46:47], 0
	v_mov_b64_e32 v[56:57], 0
	v_mov_b64_e32 v[58:59], 0
	v_mov_b64_e32 v[60:61], 0
	v_mov_b64_e32 v[62:63], 0
	v_mov_b64_e32 v[64:65], 0
	v_mov_b64_e32 v[66:67], 0
	v_mov_b64_e32 v[68:69], 0
	v_mov_b64_e32 v[70:71], 0
	v_mov_b64_e32 v[80:81], 0
	v_mov_b64_e32 v[82:83], 0
	v_mov_b64_e32 v[84:85], 0
	v_mov_b64_e32 v[86:87], 0
	v_mov_b64_e32 v[96:97], 0
	v_mov_b64_e32 v[98:99], 0
	v_mov_b64_e32 v[100:101], 0
	v_mov_b64_e32 v[102:103], 0
	v_mov_b64_e32 v[112:113], 0
	v_mov_b64_e32 v[114:115], 0
	v_mov_b64_e32 v[116:117], 0
	v_mov_b64_e32 v[118:119], 0
	v_mov_b64_e32 v[72:73], 0
	v_mov_b64_e32 v[74:75], 0
	v_mov_b64_e32 v[76:77], 0
	v_mov_b64_e32 v[78:79], 0
	v_mov_b64_e32 v[88:89], 0
	v_mov_b64_e32 v[90:91], 0
	v_mov_b64_e32 v[92:93], 0
	v_mov_b64_e32 v[94:95], 0
	v_mov_b64_e32 v[104:105], 0
	v_mov_b64_e32 v[106:107], 0
	v_mov_b64_e32 v[108:109], 0
	v_mov_b64_e32 v[110:111], 0
	v_mov_b64_e32 v[120:121], 0
	v_mov_b64_e32 v[122:123], 0
	v_mov_b64_e32 v[124:125], 0
	v_mov_b64_e32 v[126:127], 0
	s_mov_b64 s[50:51], 0x80
	s_nop 0
	s_nop 0
	s_nop 0
	s_nop 0
	s_nop 0
	s_nop 0

; template <class Epi, class Sched, bool ALIGN_EPI = false, bool SP2 = false>
; __device__ __forceinline__ void gemm_phase(PG8_LAS unsigned char* lds, const Gemm g, const Sched& S, const Epi& E) {
;     ...
;         const char* nA = has_next ? (const char*)g.A + (size_t)nxt.pm * tstep + (size_t)nxt.kt0 * kstep : cA; const char* nB = has_next ? (const char*)g.Bt + (size_t)nxt.pn * tstep + (size_t)nxt.kt0 * kstep : cB;
;         const int nt = cur.nkt;
;         for (int t = 0; t < nt; t += 2) {
;             const bool last = (t == nt - 2);
;             const char* a1 = cA + (size_t)(t + 1) * kstep;
;             const char* a2 = last ? nA : cA + (size_t)(t + 2) * kstep; const char* b2 = last ? nB : cB + (size_t)(t + 2) * kstep;
;     ...
; #pragma unroll
;         for (int a = 0; a < 2; ++a)
; #pragma unroll
;             for (int b = 0; b < 2; ++b)
; #pragma unroll
;                 for (int m = 0; m < 4; ++m)
; #pragma unroll
;                     for (int n = 0; n < 2; ++n) acc[a][b][m][n] = (f32x4){0.f, 0.f, 0.f, 0.f};
;         cur = nxt; cA = nA; cB = nB; ++ui;
.LBB0_538:
	s_ashr_i32 s13, s12, 31
	s_lshl_b64 s[14:15], s[12:13], 19
	s_add_u32 s14, s0, s14
	s_addc_u32 s15, s26, s15
	s_and_b64 s[16:17], s[8:9], exec
	s_cselect_b32 s13, s15, s23
	s_cselect_b32 s40, s14, s22
	s_ashr_i32 s11, s10, 31
	s_lshl_b64 s[16:17], s[10:11], 19
	s_add_u32 s16, s27, s16
	s_addc_u32 s17, s28, s17
	s_and_b64 s[24:25], s[8:9], exec
	s_cselect_b32 s11, s17, s21
	s_cselect_b32 s41, s16, s20
	s_add_u32 s42, s20, 0x100
	s_addc_u32 s43, s21, 0
	s_add_u32 s20, s22, 0x40080
	v_mov_b32_e32 v0, 0
	s_addc_u32 s21, s23, 0
	s_mov_b32 s45, -2
	v_mov_b64_e32 v[0:1], 0
	v_mov_b64_e32 v[2:3], 0
	v_mov_b64_e32 v[4:5], 0
	v_mov_b64_e32 v[6:7], 0
	v_mov_b64_e32 v[16:17], 0
	v_mov_b64_e32 v[18:19], 0
	v_mov_b64_e32 v[20:21], 0
	v_mov_b64_e32 v[22:23], 0
	v_mov_b64_e32 v[32:33], 0
	v_mov_b64_e32 v[34:35], 0
	v_mov_b64_e32 v[36:37], 0
	v_mov_b64_e32 v[38:39], 0
	v_mov_b64_e32 v[48:49], 0
	v_mov_b64_e32 v[50:51], 0
	v_mov_b64_e32 v[52:53], 0
	v_mov_b64_e32 v[54:55], 0
	v_mov_b64_e32 v[8:9], 0
	v_mov_b64_e32 v[10:11], 0
	v_mov_b64_e32 v[12:13], 0
	v_mov_b64_e32 v[14:15], 0
	v_mov_b64_e32 v[24:25], 0
	v_mov_b64_e32 v[26:27], 0
	v_mov_b64_e32 v[28:29], 0
	v_mov_b64_e32 v[30:31], 0
	v_mov_b64_e32 v[40:41], 0
	v_mov_b64_e32 v[42:43], 0
	v_mov_b64_e32 v[44:45], 0
	v_mov_b64_e32 v[46:47], 0
	v_mov_b64_e32 v[56:57], 0
	v_mov_b64_e32 v[58:59], 0
	v_mov_b64_e32 v[60:61], 0
	v_mov_b64_e32 v[62:63], 0
	v_mov_b64_e32 v[64:65], 0
	v_mov_b64_e32 v[66:67], 0
	v_mov_b64_e32 v[68:69], 0
	v_mov_b64_e32 v[70:71], 0
	v_mov_b64_e32 v[80:81], 0
	v_mov_b64_e32 v[82:83], 0
	v_mov_b64_e32 v[84:85], 0
	v_mov_b64_e32 v[86:87], 0
	v_mov_b64_e32 v[96:97], 0
	v_mov_b64_e32 v[98:99], 0
	v_mov_b64_e32 v[100:101], 0
	v_mov_b64_e32 v[102:103], 0
	v_mov_b64_e32 v[112:113], 0
	v_mov_b64_e32 v[114:115], 0
	v_mov_b64_e32 v[116:117], 0
	v_mov_b64_e32 v[118:119], 0
	v_mov_b64_e32 v[72:73], 0
	v_mov_b64_e32 v[74:75], 0
	v_mov_b64_e32 v[76:77], 0
	v_mov_b64_e32 v[78:79], 0
	v_mov_b64_e32 v[88:89], 0
	v_mov_b64_e32 v[90:91], 0
	v_mov_b64_e32 v[92:93], 0
	v_mov_b64_e32 v[94:95], 0
	v_mov_b64_e32 v[104:105], 0
	v_mov_b64_e32 v[106:107], 0
	v_mov_b64_e32 v[108:109], 0
	v_mov_b64_e32 v[110:111], 0
	v_mov_b64_e32 v[120:121], 0
	v_mov_b64_e32 v[122:123], 0
	v_mov_b64_e32 v[124:125], 0
	v_mov_b64_e32 v[126:127], 0
	s_mov_b64 s[50:51], 0x80
	s_nop 0
	s_nop 0
	s_nop 0
	s_nop 0
	s_nop 0
	s_nop 0
	s_nop 0
	s_nop 0
	s_nop 0
	s_nop 0
	s_nop 0

; template <class Epi, class Sched, bool ALIGN_EPI = false, bool SP2 = false>
; __device__ __forceinline__ void gemm_phase(PG8_LAS unsigned char* lds, const Gemm g, const Sched& S, const Epi& E) {
;     ...
;         const int nt = cur.nkt;
;         for (int t = 0; t < nt; t += 2) {
;             const bool last = (t == nt - 2);
;     ...
; #pragma unroll
;         for (int a = 0; a < 2; ++a)
; #pragma unroll
;             for (int b = 0; b < 2; ++b)
; #pragma unroll
;                 for (int m = 0; m < 4; ++m)
; #pragma unroll
;                     for (int n = 0; n < 2; ++n) acc[a][b][m][n] = (f32x4){0.f, 0.f, 0.f, 0.f};
;         cur = nxt; cA = nA; cB = nB; ++ui;
.LBB0_1132:
	s_add_i32 s19, s35, -2
	s_add_u32 s21, s40, 0x100
	s_addc_u32 s31, s41, 0
	s_add_u32 s16, s38, 0x40080
	v_mov_b32_e32 v0, 0
	s_addc_u32 s17, s39, 0
	s_mov_b32 s38, 0
	v_mov_b64_e32 v[0:1], 0
	v_mov_b64_e32 v[2:3], 0
	v_mov_b64_e32 v[4:5], 0
	v_mov_b64_e32 v[6:7], 0
	v_mov_b64_e32 v[8:9], 0
	v_mov_b64_e32 v[10:11], 0
	v_mov_b64_e32 v[12:13], 0
	v_mov_b64_e32 v[14:15], 0
	v_mov_b64_e32 v[16:17], 0
	v_mov_b64_e32 v[18:19], 0
	v_mov_b64_e32 v[20:21], 0
	v_mov_b64_e32 v[22:23], 0
	v_mov_b64_e32 v[24:25], 0
	v_mov_b64_e32 v[26:27], 0
	v_mov_b64_e32 v[28:29], 0
	v_mov_b64_e32 v[30:31], 0
	v_mov_b64_e32 v[32:33], 0
	v_mov_b64_e32 v[34:35], 0
	v_mov_b64_e32 v[36:37], 0
	v_mov_b64_e32 v[38:39], 0
	v_mov_b64_e32 v[40:41], 0
	v_mov_b64_e32 v[42:43], 0
	v_mov_b64_e32 v[44:45], 0
	v_mov_b64_e32 v[46:47], 0
	v_mov_b64_e32 v[48:49], 0
	v_mov_b64_e32 v[50:51], 0
	v_mov_b64_e32 v[52:53], 0
	v_mov_b64_e32 v[54:55], 0
	v_mov_b64_e32 v[56:57], 0
	v_mov_b64_e32 v[58:59], 0
	v_mov_b64_e32 v[60:61], 0
	v_mov_b64_e32 v[62:63], 0
	v_mov_b64_e32 v[64:65], 0
	v_mov_b64_e32 v[66:67], 0
	v_mov_b64_e32 v[68:69], 0
	v_mov_b64_e32 v[70:71], 0
	v_mov_b64_e32 v[72:73], 0
	v_mov_b64_e32 v[74:75], 0
	v_mov_b64_e32 v[76:77], 0
	v_mov_b64_e32 v[78:79], 0
	v_mov_b64_e32 v[80:81], 0
	v_mov_b64_e32 v[82:83], 0
	v_mov_b64_e32 v[84:85], 0
	v_mov_b64_e32 v[86:87], 0
	v_mov_b64_e32 v[88:89], 0
	v_mov_b64_e32 v[90:91], 0
	v_mov_b64_e32 v[92:93], 0
	v_mov_b64_e32 v[94:95], 0
	v_mov_b64_e32 v[96:97], 0
	v_mov_b64_e32 v[98:99], 0
	v_mov_b64_e32 v[100:101], 0
	v_mov_b64_e32 v[102:103], 0
	v_mov_b64_e32 v[104:105], 0
	v_mov_b64_e32 v[106:107], 0
	v_mov_b64_e32 v[108:109], 0
	v_mov_b64_e32 v[110:111], 0
	v_mov_b64_e32 v[112:113], 0
	v_mov_b64_e32 v[114:115], 0
	v_mov_b64_e32 v[116:117], 0
	v_mov_b64_e32 v[118:119], 0
	v_mov_b64_e32 v[120:121], 0
	s_waitcnt vmcnt(0)
	v_mov_b32_e32 v122, v0
	v_mov_b32_e32 v123, v0
	v_mov_b32_e32 v124, v0
	v_mov_b32_e32 v125, v0
	v_mov_b32_e32 v126, v0
	v_mov_b32_e32 v127, v0
	s_mov_b64 s[66:67], 0x80
	s_nop 0
	s_nop 0

; template <class Epi, class Sched, bool ALIGN_EPI = false, bool SP2 = false>
; __device__ __forceinline__ void gemm_phase(PG8_LAS unsigned char* lds, const Gemm g, const Sched& S, const Epi& E) {
;     ...
;         const char* nA = has_next ? (const char*)g.A + (size_t)nxt.pm * tstep + (size_t)nxt.kt0 * kstep : cA; const char* nB = has_next ? (const char*)g.Bt + (size_t)nxt.pn * tstep + (size_t)nxt.kt0 * kstep : cB;
;         const int nt = cur.nkt;
;         for (int t = 0; t < nt; t += 2) {
;             const bool last = (t == nt - 2);
;             const char* a1 = cA + (size_t)(t + 1) * kstep;
;             const char* a2 = last ? nA : cA + (size_t)(t + 2) * kstep; const char* b2 = last ? nB : cB + (size_t)(t + 2) * kstep;
;     ...
; #pragma unroll
;         for (int a = 0; a < 2; ++a)
; #pragma unroll
;             for (int b = 0; b < 2; ++b)
; #pragma unroll
;                 for (int m = 0; m < 4; ++m)
; #pragma unroll
;                     for (int n = 0; n < 2; ++n) acc[a][b][m][n] = (f32x4){0.f, 0.f, 0.f, 0.f};
;         cur = nxt; cA = nA; cB = nB; ++ui;
.LBB0_1204:
	s_ashr_i32 s17, s16, 31
	s_lshl_b64 s[18:19], s[16:17], 19
	s_add_u32 s18, s44, s18
	s_addc_u32 s19, s45, s19
	s_and_b64 s[20:21], s[12:13], exec
	s_cselect_b32 s17, s19, s29
	s_cselect_b32 s23, s18, s28
	s_ashr_i32 s15, s14, 31
	s_lshl_b64 s[20:21], s[14:15], 19
	s_add_u32 s20, s46, s20
	s_addc_u32 s21, s47, s21
	s_and_b64 s[30:31], s[12:13], exec
	s_cselect_b32 s15, s21, s27
	s_cselect_b32 s42, s20, s26
	s_add_u32 s43, s26, 0x100
	s_addc_u32 s48, s27, 0
	s_add_u32 s26, s28, 0x40080
	v_mov_b32_e32 v0, 0
	s_addc_u32 s27, s29, 0
	s_mov_b32 s49, -2
	s_waitcnt lgkmcnt(0)
	v_mov_b64_e32 v[0:1], 0
	v_mov_b64_e32 v[2:3], 0
	v_mov_b64_e32 v[4:5], 0
	v_mov_b64_e32 v[6:7], 0
	v_mov_b64_e32 v[16:17], 0
	v_mov_b64_e32 v[18:19], 0
	v_mov_b64_e32 v[20:21], 0
	v_mov_b64_e32 v[22:23], 0
	v_mov_b64_e32 v[32:33], 0
	v_mov_b64_e32 v[34:35], 0
	v_mov_b64_e32 v[36:37], 0
	v_mov_b64_e32 v[38:39], 0
	v_mov_b64_e32 v[48:49], 0
	v_mov_b64_e32 v[50:51], 0
	v_mov_b64_e32 v[52:53], 0
	v_mov_b64_e32 v[54:55], 0
	v_mov_b64_e32 v[8:9], 0
	v_mov_b64_e32 v[10:11], 0
	v_mov_b64_e32 v[12:13], 0
	v_mov_b64_e32 v[14:15], 0
	v_mov_b64_e32 v[24:25], 0
	v_mov_b64_e32 v[26:27], 0
	v_mov_b64_e32 v[28:29], 0
	v_mov_b64_e32 v[30:31], 0
	v_mov_b64_e32 v[40:41], 0
	v_mov_b64_e32 v[42:43], 0
	v_mov_b64_e32 v[44:45], 0
	v_mov_b64_e32 v[46:47], 0
	v_mov_b64_e32 v[56:57], 0
	v_mov_b64_e32 v[58:59], 0
	v_mov_b64_e32 v[60:61], 0
	v_mov_b64_e32 v[62:63], 0
	v_mov_b64_e32 v[64:65], 0
	v_mov_b64_e32 v[66:67], 0
	v_mov_b64_e32 v[68:69], 0
	v_mov_b64_e32 v[70:71], 0
	v_mov_b64_e32 v[80:81], 0
	v_mov_b64_e32 v[82:83], 0
	v_mov_b64_e32 v[84:85], 0
	v_mov_b64_e32 v[86:87], 0
	v_mov_b64_e32 v[96:97], 0
	v_mov_b64_e32 v[98:99], 0
	v_mov_b64_e32 v[100:101], 0
	v_mov_b64_e32 v[102:103], 0
	v_mov_b64_e32 v[112:113], 0
	v_mov_b64_e32 v[114:115], 0
	v_mov_b64_e32 v[116:117], 0
	v_mov_b64_e32 v[118:119], 0
	v_mov_b64_e32 v[72:73], 0
	v_mov_b64_e32 v[74:75], 0
	v_mov_b64_e32 v[76:77], 0
	v_mov_b64_e32 v[78:79], 0
	v_mov_b64_e32 v[88:89], 0
	v_mov_b64_e32 v[90:91], 0
	v_mov_b64_e32 v[92:93], 0
	v_mov_b64_e32 v[94:95], 0
	v_mov_b64_e32 v[104:105], 0
	v_mov_b64_e32 v[106:107], 0
	v_mov_b64_e32 v[108:109], 0
	v_mov_b64_e32 v[110:111], 0
	v_mov_b64_e32 v[120:121], 0
	s_waitcnt vmcnt(0)
	v_mov_b32_e32 v122, v0
	v_mov_b32_e32 v123, v0
	v_mov_b32_e32 v124, v0
	v_mov_b32_e32 v125, v0
	v_mov_b32_e32 v126, v0
	v_mov_b32_e32 v127, v0
	s_mov_b64 s[54:55], 0x80
	s_nop 0
	s_nop 0

; template <class Epi, class Sched, bool ALIGN_EPI = false, bool SP2 = false>
; __device__ __forceinline__ void gemm_phase(PG8_LAS unsigned char* lds, const Gemm g, const Sched& S, const Epi& E) {
;     ...
;         const char* nA = has_next ? (const char*)g.A + (size_t)nxt.pm * tstep + (size_t)nxt.kt0 * kstep : cA; const char* nB = has_next ? (const char*)g.Bt + (size_t)nxt.pn * tstep + (size_t)nxt.kt0 * kstep : cB;
;         const int nt = cur.nkt;
;         for (int t = 0; t < nt; t += 2) {
;             const bool last = (t == nt - 2);
;             const char* a1 = cA + (size_t)(t + 1) * kstep;
;             const char* a2 = last ? nA : cA + (size_t)(t + 2) * kstep; const char* b2 = last ? nB : cB + (size_t)(t + 2) * kstep;
;     ...
; #pragma unroll
;         for (int a = 0; a < 2; ++a)
; #pragma unroll
;             for (int b = 0; b < 2; ++b)
; #pragma unroll
;                 for (int m = 0; m < 4; ++m)
; #pragma unroll
;                     for (int n = 0; n < 2; ++n) acc[a][b][m][n] = (f32x4){0.f, 0.f, 0.f, 0.f};
;         cur = nxt; cA = nA; cB = nB; ++ui;
.LBB0_1294:
	s_ashr_i32 s17, s16, 31
	s_lshl_b64 s[18:19], s[16:17], 19
	s_add_u32 s18, s0, s18
	s_addc_u32 s19, s28, s19
	s_and_b64 s[20:21], s[6:7], exec
	s_cselect_b32 s17, s19, s25
	s_cselect_b32 s42, s18, s24
	s_ashr_i32 s15, s14, 31
	s_lshl_b64 s[20:21], s[14:15], 19
	s_add_u32 s20, s29, s20
	s_addc_u32 s21, s30, s21
	s_and_b64 s[26:27], s[6:7], exec
	s_cselect_b32 s15, s21, s23
	s_cselect_b32 s43, s20, s22
	s_add_u32 s44, s22, 0x100
	s_addc_u32 s45, s23, 0
	s_add_u32 s22, s24, 0x40080
	v_mov_b32_e32 v0, 0
	s_addc_u32 s23, s25, 0
	s_mov_b32 s46, -2
	v_mov_b64_e32 v[0:1], 0
	v_mov_b64_e32 v[2:3], 0
	v_mov_b64_e32 v[8:9], 0
	v_mov_b64_e32 v[10:11], 0
	v_mov_b64_e32 v[16:17], 0
	v_mov_b64_e32 v[18:19], 0
	v_mov_b64_e32 v[24:25], 0
	v_mov_b64_e32 v[26:27], 0
	v_mov_b64_e32 v[32:33], 0
	v_mov_b64_e32 v[34:35], 0
	v_mov_b64_e32 v[40:41], 0
	v_mov_b64_e32 v[42:43], 0
	v_mov_b64_e32 v[48:49], 0
	v_mov_b64_e32 v[50:51], 0
	v_mov_b64_e32 v[56:57], 0
	v_mov_b64_e32 v[58:59], 0
	v_mov_b64_e32 v[4:5], 0
	v_mov_b64_e32 v[6:7], 0
	v_mov_b64_e32 v[12:13], 0
	v_mov_b64_e32 v[14:15], 0
	v_mov_b64_e32 v[20:21], 0
	v_mov_b64_e32 v[22:23], 0
	v_mov_b64_e32 v[28:29], 0
	v_mov_b64_e32 v[30:31], 0
	v_mov_b64_e32 v[36:37], 0
	v_mov_b64_e32 v[38:39], 0
	v_mov_b64_e32 v[44:45], 0
	v_mov_b64_e32 v[46:47], 0
	v_mov_b64_e32 v[52:53], 0
	v_mov_b64_e32 v[54:55], 0
	v_mov_b64_e32 v[60:61], 0
	v_mov_b64_e32 v[62:63], 0
	v_mov_b64_e32 v[64:65], 0
	v_mov_b64_e32 v[66:67], 0
	v_mov_b64_e32 v[72:73], 0
	v_mov_b64_e32 v[74:75], 0
	v_mov_b64_e32 v[80:81], 0
	v_mov_b64_e32 v[82:83], 0
	v_mov_b64_e32 v[88:89], 0
	v_mov_b64_e32 v[90:91], 0
	v_mov_b64_e32 v[96:97], 0
	v_mov_b64_e32 v[98:99], 0
	v_mov_b64_e32 v[104:105], 0
	v_mov_b64_e32 v[106:107], 0
	v_mov_b64_e32 v[112:113], 0
	v_mov_b64_e32 v[114:115], 0
	v_mov_b64_e32 v[120:121], 0
	v_mov_b64_e32 v[122:123], 0
	v_mov_b64_e32 v[68:69], 0
	v_mov_b64_e32 v[70:71], 0
	v_mov_b64_e32 v[76:77], 0
	v_mov_b64_e32 v[78:79], 0
	v_mov_b64_e32 v[84:85], 0
	v_mov_b64_e32 v[86:87], 0
	v_mov_b64_e32 v[92:93], 0
	v_mov_b64_e32 v[94:95], 0
	v_mov_b64_e32 v[100:101], 0
	v_mov_b64_e32 v[102:103], 0
	v_mov_b64_e32 v[108:109], 0
	v_mov_b64_e32 v[110:111], 0
	v_mov_b64_e32 v[116:117], 0
	v_mov_b64_e32 v[118:119], 0
	v_mov_b64_e32 v[124:125], 0
	v_mov_b64_e32 v[126:127], 0
	s_mov_b64 s[52:53], 0x80
	s_nop 0
	s_nop 0
	s_nop 0

; template <class Epi, class Sched, bool ALIGN_EPI = false, bool SP2 = false>
; __device__ __forceinline__ void gemm_phase(PG8_LAS unsigned char* lds, const Gemm g, const Sched& S, const Epi& E) {
;     ...
;         const int nt = cur.nkt;
;         for (int t = 0; t < nt; t += 2) {
;             const bool last = (t == nt - 2);
;     ...
; #pragma unroll
;         for (int a = 0; a < 2; ++a)
; #pragma unroll
;             for (int b = 0; b < 2; ++b)
; #pragma unroll
;                 for (int m = 0; m < 4; ++m)
; #pragma unroll
;                     for (int n = 0; n < 2; ++n) acc[a][b][m][n] = (f32x4){0.f, 0.f, 0.f, 0.f};
;         cur = nxt; cA = nA; cB = nB; ++ui;
.LBB0_1377:
	s_add_i32 s25, s27, -2
	s_add_u32 s57, s34, 0x100
	v_mov_b32_e32 v0, 0
	s_addc_u32 s58, s35, 0
	s_mov_b32 s34, 0
	v_mov_b64_e32 v[0:1], 0
	v_mov_b64_e32 v[2:3], 0
	v_mov_b64_e32 v[4:5], 0
	v_mov_b64_e32 v[6:7], 0
	v_mov_b64_e32 v[8:9], 0
	v_mov_b64_e32 v[10:11], 0
	v_mov_b64_e32 v[12:13], 0
	v_mov_b64_e32 v[14:15], 0
	v_mov_b64_e32 v[16:17], 0
	v_mov_b64_e32 v[18:19], 0
	v_mov_b64_e32 v[20:21], 0
	v_mov_b64_e32 v[22:23], 0
	v_mov_b64_e32 v[24:25], 0
	v_mov_b64_e32 v[26:27], 0
	v_mov_b64_e32 v[28:29], 0
	v_mov_b64_e32 v[30:31], 0
	v_mov_b64_e32 v[32:33], 0
	v_mov_b64_e32 v[34:35], 0
	v_mov_b64_e32 v[36:37], 0
	v_mov_b64_e32 v[38:39], 0
	v_mov_b64_e32 v[40:41], 0
	v_mov_b64_e32 v[42:43], 0
	v_mov_b64_e32 v[44:45], 0
	v_mov_b64_e32 v[46:47], 0
	v_mov_b64_e32 v[48:49], 0
	v_mov_b64_e32 v[50:51], 0
	v_mov_b64_e32 v[52:53], 0
	v_mov_b64_e32 v[54:55], 0
	v_mov_b64_e32 v[56:57], 0
	v_mov_b64_e32 v[58:59], 0
	v_mov_b64_e32 v[60:61], 0
	v_mov_b64_e32 v[62:63], 0
	v_mov_b64_e32 v[64:65], 0
	v_mov_b64_e32 v[66:67], 0
	v_mov_b64_e32 v[68:69], 0
	v_mov_b64_e32 v[70:71], 0
	v_mov_b64_e32 v[72:73], 0
	v_mov_b64_e32 v[74:75], 0
	v_mov_b64_e32 v[76:77], 0
	v_mov_b64_e32 v[78:79], 0
	v_mov_b64_e32 v[80:81], 0
	v_mov_b64_e32 v[82:83], 0
	v_mov_b64_e32 v[84:85], 0
	v_mov_b64_e32 v[86:87], 0
	v_mov_b64_e32 v[88:89], 0
	v_mov_b64_e32 v[90:91], 0
	v_mov_b64_e32 v[92:93], 0
	v_mov_b64_e32 v[94:95], 0
	v_mov_b64_e32 v[96:97], 0
	v_mov_b64_e32 v[98:99], 0
	v_mov_b64_e32 v[100:101], 0
	v_mov_b64_e32 v[102:103], 0
	v_mov_b64_e32 v[104:105], 0
	v_mov_b64_e32 v[106:107], 0
	v_mov_b64_e32 v[108:109], 0
	v_mov_b64_e32 v[110:111], 0
	v_mov_b64_e32 v[112:113], 0
	v_mov_b64_e32 v[114:115], 0
	v_mov_b64_e32 v[116:117], 0
	v_mov_b64_e32 v[118:119], 0
	v_mov_b64_e32 v[120:121], 0
	v_mov_b64_e32 v[122:123], 0
	v_mov_b64_e32 v[124:125], 0
	v_mov_b64_e32 v[126:127], 0
	s_mov_b64 s[62:63], 0x80
	s_nop 0
	s_nop 0
	s_nop 0
	s_nop 0
	s_nop 0

; template <class Epi, class Sched, bool ALIGN_EPI = false, bool SP2 = false>
; __device__ __forceinline__ void gemm_phase(PG8_LAS unsigned char* lds, const Gemm g, const Sched& S, const Epi& E) {
;     ...
; #pragma unroll
;         for (int a = 0; a < 2; ++a)
; #pragma unroll
;             for (int b = 0; b < 2; ++b)
; #pragma unroll
;                 for (int m = 0; m < 4; ++m)
; #pragma unroll
;                     for (int n = 0; n < 2; ++n) acc[a][b][m][n] = (f32x4){0.f, 0.f, 0.f, 0.f};
;         cur = nxt; cA = nA; cB = nB; ++ui;
.LBB0_1453:
	s_add_u32 s42, s18, 0x100
	v_mov_b32_e32 v0, 0
	s_addc_u32 s43, s19, 0
	s_mov_b32 s44, -2
	s_waitcnt lgkmcnt(0)
	v_mov_b64_e32 v[0:1], 0
	v_mov_b64_e32 v[2:3], 0
	v_mov_b64_e32 v[4:5], 0
	v_mov_b64_e32 v[6:7], 0
	v_mov_b64_e32 v[16:17], 0
	v_mov_b64_e32 v[18:19], 0
	v_mov_b64_e32 v[20:21], 0
	v_mov_b64_e32 v[22:23], 0
	v_mov_b64_e32 v[32:33], 0
	v_mov_b64_e32 v[34:35], 0
	v_mov_b64_e32 v[36:37], 0
	v_mov_b64_e32 v[38:39], 0
	v_mov_b64_e32 v[48:49], 0
	v_mov_b64_e32 v[50:51], 0
	v_mov_b64_e32 v[52:53], 0
	v_mov_b64_e32 v[54:55], 0
	v_mov_b64_e32 v[8:9], 0
	v_mov_b64_e32 v[10:11], 0
	v_mov_b64_e32 v[12:13], 0
	v_mov_b64_e32 v[14:15], 0
	v_mov_b64_e32 v[24:25], 0
	v_mov_b64_e32 v[26:27], 0
	v_mov_b64_e32 v[28:29], 0
	v_mov_b64_e32 v[30:31], 0
	v_mov_b64_e32 v[40:41], 0
	v_mov_b64_e32 v[42:43], 0
	v_mov_b64_e32 v[44:45], 0
	v_mov_b64_e32 v[46:47], 0
	v_mov_b64_e32 v[56:57], 0
	v_mov_b64_e32 v[58:59], 0
	v_mov_b64_e32 v[60:61], 0
	v_mov_b64_e32 v[62:63], 0
	v_mov_b64_e32 v[64:65], 0
	v_mov_b64_e32 v[66:67], 0
	v_mov_b64_e32 v[68:69], 0
	v_mov_b64_e32 v[70:71], 0
	v_mov_b64_e32 v[80:81], 0
	v_mov_b64_e32 v[82:83], 0
	v_mov_b64_e32 v[84:85], 0
	v_mov_b64_e32 v[86:87], 0
	v_mov_b64_e32 v[96:97], 0
	v_mov_b64_e32 v[98:99], 0
	v_mov_b64_e32 v[100:101], 0
	v_mov_b64_e32 v[102:103], 0
	v_mov_b64_e32 v[112:113], 0
	v_mov_b64_e32 v[114:115], 0
	v_mov_b64_e32 v[116:117], 0
	v_mov_b64_e32 v[118:119], 0
	v_mov_b64_e32 v[72:73], 0
	v_mov_b64_e32 v[74:75], 0
	v_mov_b64_e32 v[76:77], 0
	v_mov_b64_e32 v[78:79], 0
	v_mov_b64_e32 v[88:89], 0
	v_mov_b64_e32 v[90:91], 0
	v_mov_b64_e32 v[92:93], 0
	v_mov_b64_e32 v[94:95], 0
	v_mov_b64_e32 v[104:105], 0
	v_mov_b64_e32 v[106:107], 0
	v_mov_b64_e32 v[108:109], 0
	v_mov_b64_e32 v[110:111], 0
	v_mov_b64_e32 v[120:121], 0
	v_mov_b64_e32 v[122:123], 0
	v_mov_b64_e32 v[124:125], 0
	v_mov_b64_e32 v[126:127], 0
	s_mov_b64 s[48:49], 0x80
	s_nop 0
	s_nop 0
	s_nop 0
	s_nop 0
	s_nop 0
